# code placement: four 4-byte pads in once-per-phase code so every hot loop head (scan, ret_out, GEMM main loops) sits at an 8-byte phase, on top of v86
# speedup vs baseline: 1.0104x; 1.0104x over previous
; #define PG8_WAIT_V(n) asm volatile("s_waitcnt vmcnt(" #n ")" ::: "memory")
; #define PG8_BAR __builtin_amdgcn_s_barrier()
; template <class Epi, class Sched, bool ALIGN_EPI = false, bool SP2 = false>
; __device__ __forceinline__ void gemm_phase(PG8_LAS unsigned char* lds, const Gemm g, const Sched& S, const Epi& E) {
;     ...
;     PG8_WAIT_V(0);
;     if constexpr (!ALIGN_EPI) { if (wr == 0) PG8_BAR; }
;     PG8_BAR;
.LBB0_564:
	s_nop 0
	s_waitcnt vmcnt(0)
	v_readlane_b32 s56, v255, 4
	v_readlane_b32 s58, v255, 6
	v_readlane_b32 s52, v255, 8
	v_readlane_b32 s57, v255, 5
	v_readlane_b32 s59, v255, 7
	v_readlane_b32 s53, v255, 9
	v_readlane_b32 s55, v255, 10
	s_barrier

; __device__ __forceinline__ float head_log2_gamma(int h) { return __builtin_log2f(1.0f - __builtin_exp2f(-5.0f - (float)h)); }
; #define R2_LOADS(src, rstride, sl) do { _Pragma("unroll") for (int i = 0; i < 4; ++i) sr[i] = *(const v4u*)((src) + (size_t)(srow + 128 * i) * (rstride) + 32 * (sl) + 8 * sc4); } while (0)
; #define R2_STORES(bf) do { _Pragma("unroll") for (int i = 0; i < 4; ++i) *(LAS v4u*)(lds + (bf) * R2_SBUF + sso + 128 * i * 64) = sr[i]; } while (0)
;     ...
;         const int bh = task >> 6, c = (task & 63) ^ (task >> 8), h = bh & 3, odd = c & 1, tk0 = (c & ~1) * 128, tq0 = c * 128;
;         const float lg2 = head_log2_gamma(h);
;         f32x16 acc[8];
; #pragma unroll
;         for (int et = 0; et < 8; ++et)
; #pragma unroll
;             for (int i = 0; i < 16; ++i) acc[et][i] = 0.f;
;         v4u sr[4];
;     ...
;         if (!(dry && (R2_SKIP & 1))) { R2_IDS const bf16* qg = R2_QG; const bf16* src = ST + (((size_t)(bh * 32 + (c >> 1))) * 512) * 256;
;           __syncthreads();
;           R2_LOADS(src, 256, 0); R2_STORES(0);
;           __syncthreads();
;           for (int sl = 0; sl < 8; ++sl) {
;               if (sl + 1 < 8) R2_LOADS(src, 256, sl + 1);
;               const bf16x8_t bq0 = *(const bf16x8_t*)(qg + 32 * sl), bq1 = *(const bf16x8_t*)(qg + 32 * sl + 16);
;               R2_SLICE(sl & 1, bq0, bq1);
;               if (sl + 1 < 8) R2_STORES((sl + 1) & 1);
;               __syncthreads();
;           } }
.LBB0_718:
	s_ashr_i32 s7, s36, 6
	s_and_b32 s4, s36, 63
	s_ashr_i32 s5, s36, 8
	s_xor_b32 s40, s4, s5
	s_and_b32 s4, s7, 3
	s_waitcnt vmcnt(0)
	v_cvt_f32_ubyte0_e32 v0, s4
	v_sub_f32_e32 v0, 0xc0a00000, v0
	s_mov_b32 s6, 0xc2fc0000
	v_cmp_gt_f32_e32 vcc, s6, v0
	s_lshl_b32 s5, s40, 7
	s_and_b64 s[34:35], vcc, exec
	v_cndmask_b32_e32 v1, 0, v235, vcc
	v_add_f32_e32 v0, v0, v1
	v_exp_f32_e32 v0, v0
	s_cselect_b32 s6, 0xffffffc0, 0
	v_mov_b32_e32 v20, v33
	s_lshl_b32 s34, s7, 5
	v_ldexp_f32 v0, v0, s6
	s_ashr_i32 s35, s40, 1
	v_sub_f32_e32 v140, 1.0, v0
	s_lshl_b32 s41, s7, 13
	v_and_b32_e32 v0, 31, v20
	s_add_i32 s34, s35, s34
	v_or_b32_e32 v24, s30, v0
	s_add_i32 s19, s5, s41
	v_or_b32_e32 v0, s47, v0
	s_ashr_i32 s35, s34, 31
	s_and_b32 s6, s5, 0xffffff00
	v_or_b32_e32 v0, s19, v0
	s_lshl_b64 s[34:35], s[34:35], 18
	v_ashrrev_i32_e32 v16, 2, v20
	v_lshlrev_b32_e32 v2, 4, v20
	v_ashrrev_i32_e32 v1, 31, v0
	s_add_u32 s34, s43, s34
	v_lshlrev_b64 v[18:19], 9, v[0:1]
	s_addc_u32 s35, s44, s35
	v_and_b32_e32 v0, 48, v2
	v_mov_b32_e32 v1, v32
	v_ashrrev_i32_e32 v17, 31, v16
	v_bitop3_b32 v23, v2, 48, v20 bitop3:0x48
	v_lshl_add_u64 v[0:1], s[34:35], 0, v[0:1]
	v_lshlrev_b64 v[2:3], 9, v[16:17]
	v_lshl_add_u64 v[130:131], v[0:1], 0, v[2:3]
	s_mov_b64 s[34:35], 0x10000
	v_lshl_add_u64 v[132:133], v[130:131], 0, s[34:35]
	s_mov_b32 s34, 0x10000
	v_add_co_u32_e32 v4, vcc, s34, v130
	s_mov_b32 s34, 0x20000
	s_nop 0
	v_addc_co_u32_e32 v5, vcc, 0, v131, vcc
	v_add_co_u32_e32 v8, vcc, s34, v130
	s_mov_b64 s[34:35], 0x30000
	s_barrier
	global_load_dwordx4 v[0:3], v[130:131], off
	v_addc_co_u32_e32 v9, vcc, 0, v131, vcc
	v_lshl_add_u64 v[136:137], v[130:131], 0, s[34:35]
	s_mov_b32 s34, 0x30000
	global_load_dwordx4 v[4:7], v[4:5], off
	v_add_co_u32_e32 v12, vcc, s34, v130
	global_load_dwordx4 v[8:11], v[8:9], off
	s_nop 0
	v_addc_co_u32_e32 v13, vcc, 0, v131, vcc
	global_load_dwordx4 v[12:15], v[12:13], off
	v_lshl_add_u32 v16, v16, 6, 0
	s_mov_b32 s34, 0x10800
	v_bfe_u32 v22, v20, 5, 1
	v_add3_u32 v141, v16, v23, s34
	v_lshl_add_u64 v[18:19], s[24:25], 0, v[18:19]
	v_lshl_add_u64 v[134:135], v[130:131], 0, s[12:13]
	v_lshrrev_b32_e32 v21, 5, v20
	v_bfe_u32 v17, v20, 2, 2
	v_lshl_add_u32 v147, v24, 6, 0
	s_and_b32 s40, s40, 1
	s_waitcnt vmcnt(3)
	ds_write_b128 v141, v[0:3]
	s_waitcnt vmcnt(2)
	ds_write_b128 v141, v[4:7] offset:8192
	s_waitcnt vmcnt(1)
	ds_write_b128 v141, v[8:11] offset:16384
	s_waitcnt vmcnt(0)
	ds_write_b128 v141, v[12:15] offset:24576
	v_lshlrev_b32_e32 v0, 4, v22
	v_mov_b32_e32 v1, v32
	v_lshl_add_u64 v[138:139], v[18:19], 0, v[0:1]
	s_waitcnt lgkmcnt(0)
	s_barrier
	global_load_dwordx4 v[148:151], v[130:131], off offset:64
	global_load_dwordx4 v[152:155], v[132:133], off offset:64
	global_load_dwordx4 v[156:159], v[134:135], off offset:64
	global_load_dwordx4 v[160:163], v[136:137], off offset:64
	global_load_dwordx4 v[50:53], v[138:139], off
	global_load_dwordx4 v[164:167], v[138:139], off offset:32
	v_bitop3_b32 v0, v21, v17, 1 bitop3:0x6c
	v_lshlrev_b32_e32 v192, 4, v0
	v_bitop3_b32 v0, v22, v17, 2 bitop3:0x36
	v_lshlrev_b32_e32 v193, 4, v0
	v_add_u32_e32 v4, 0x10800, v147
	v_add_u32_e32 v142, v4, v192
	v_add_u32_e32 v143, v4, v193
	ds_read_b128 v[0:3], v142
	ds_read_b128 v[16:19], v143
	v_add_u32_e32 v4, 0x11000, v147
	v_add_u32_e32 v144, v4, v192
	v_add_u32_e32 v145, v4, v193
	ds_read_b128 v[20:23], v144
	ds_read_b128 v[34:37], v145
	v_add_u32_e32 v4, 0x11800, v147
	v_add_u32_e32 v146, v4, v192
	v_add_u32_e32 v195, v4, v193
	ds_read_b128 v[38:41], v146
	ds_read_b128 v[54:57], v195
	s_waitcnt vmcnt(1) lgkmcnt(5)
	v_mfma_f32_32x32x16_bf16 v[0:15], v[0:3], v[50:53], 0
	s_waitcnt vmcnt(0) lgkmcnt(4)
	v_mfma_f32_32x32x16_bf16 v[0:15], v[16:19], v[164:167], v[0:15]
	v_add_u32_e32 v16, 0x12000, v147
	v_add_u32_e32 v208, v16, v192
	v_add_u32_e32 v209, v16, v193
	ds_read_b128 v[58:61], v208
	ds_read_b128 v[62:65], v209
	s_waitcnt lgkmcnt(5)
	v_mfma_f32_32x32x16_bf16 v[16:31], v[20:23], v[50:53], 0
	s_waitcnt lgkmcnt(4)
	v_mfma_f32_32x32x16_bf16 v[16:31], v[34:37], v[164:167], v[16:31]
	v_add_u32_e32 v34, 0x12800, v147
	v_add_u32_e32 v210, v34, v192
	v_add_u32_e32 v211, v34, v193
	ds_read_b128 v[82:85], v210
	ds_read_b128 v[86:89], v211
	s_waitcnt lgkmcnt(5)
	v_mfma_f32_32x32x16_bf16 v[34:49], v[38:41], v[50:53], 0
	s_waitcnt lgkmcnt(4)
	v_mfma_f32_32x32x16_bf16 v[34:49], v[54:57], v[164:167], v[34:49]
	v_add_u32_e32 v54, 0x13000, v147
	v_add_u32_e32 v212, v54, v192
	v_add_u32_e32 v213, v54, v193
	ds_read_b128 v[54:57], v212
	ds_read_b128 v[90:93], v213
	s_waitcnt lgkmcnt(5)
	v_mfma_f32_32x32x16_bf16 v[66:81], v[58:61], v[50:53], 0
	s_waitcnt lgkmcnt(4)
	v_mfma_f32_32x32x16_bf16 v[66:81], v[62:65], v[164:167], v[66:81]
	v_add_u32_e32 v58, 0x13800, v147
	v_add_u32_e32 v214, v58, v192
	v_add_u32_e32 v215, v58, v193
	ds_read_b128 v[58:61], v214
	ds_read_b128 v[62:65], v215
	s_waitcnt lgkmcnt(5)
	v_mfma_f32_32x32x16_bf16 v[98:113], v[82:85], v[50:53], 0
	s_waitcnt lgkmcnt(4)
	v_mfma_f32_32x32x16_bf16 v[98:113], v[86:89], v[164:167], v[98:113]
	v_add_u32_e32 v82, 0x14000, v147
	v_add_u32_e32 v216, v82, v192
	v_add_u32_e32 v217, v82, v193
	ds_read_b128 v[168:171], v216
	ds_read_b128 v[172:175], v217
	s_waitcnt lgkmcnt(5)
	v_mfma_f32_32x32x16_bf16 v[114:129], v[54:57], v[50:53], 0
	s_waitcnt lgkmcnt(4)
	v_mfma_f32_32x32x16_bf16 v[114:129], v[90:93], v[164:167], v[114:129]
	s_waitcnt lgkmcnt(3)
	v_mfma_f32_32x32x16_bf16 v[82:97], v[58:61], v[50:53], 0
	s_waitcnt lgkmcnt(2)
	v_mfma_f32_32x32x16_bf16 v[82:97], v[62:65], v[164:167], v[82:97]
	s_waitcnt lgkmcnt(1)
	v_mfma_f32_32x32x16_bf16 v[50:65], v[168:171], v[50:53], 0
	s_waitcnt lgkmcnt(0)
	v_mfma_f32_32x32x16_bf16 v[50:65], v[172:175], v[164:167], v[50:65]
	ds_write_b128 v141, v[148:151] offset:32768
	ds_write_b128 v141, v[152:155] offset:40960
	ds_write_b128 v141, v[156:159] offset:49152
	ds_write_b128 v141, v[160:163] offset:57344
	s_waitcnt lgkmcnt(0)
	s_barrier
; #define R2_LOADS(src, rstride, sl) do { _Pragma("unroll") for (int i = 0; i < 4; ++i) sr[i] = *(const v4u*)((src) + (size_t)(srow + 128 * i) * (rstride) + 32 * (sl) + 8 * sc4); } while (0)
; #define R2_STORES(bf) do { _Pragma("unroll") for (int i = 0; i < 4; ++i) *(LAS v4u*)(lds + (bf) * R2_SBUF + sso + 128 * i * 64) = sr[i]; } while (0)
;     ...
;           for (int sl = 0; sl < 8; ++sl) {
;               if (sl + 1 < 8) R2_LOADS(src, 256, sl + 1);
;               const bf16x8_t bq0 = *(const bf16x8_t*)(qg + 32 * sl), bq1 = *(const bf16x8_t*)(qg + 32 * sl + 16);
;               R2_SLICE(sl & 1, bq0, bq1);
;               if (sl + 1 < 8) R2_STORES((sl + 1) & 1);
;               __syncthreads();
;           } }
	global_load_dwordx4 v[148:151], v[130:131], off offset:128
	global_load_dwordx4 v[152:155], v[132:133], off offset:128
	global_load_dwordx4 v[156:159], v[134:135], off offset:128
	global_load_dwordx4 v[160:163], v[136:137], off offset:128
	global_load_dwordx4 v[164:167], v[138:139], off offset:64
	global_load_dwordx4 v[168:171], v[138:139], off offset:96
	v_add_u32_e32 v172, 0x18800, v147
	v_add_u32_e32 v218, v172, v192
	v_add_u32_e32 v219, v172, v193
	ds_read_b128 v[172:175], v218
	ds_read_b128 v[176:179], v219
	v_add_u32_e32 v180, 0x19000, v147
	v_add_u32_e32 v220, v180, v192
	v_add_u32_e32 v221, v180, v193
	ds_read_b128 v[180:183], v220
	ds_read_b128 v[184:187], v221
	v_add_u32_e32 v188, 0x19800, v147
	v_add_u32_e32 v222, v188, v192
	v_add_u32_e32 v223, v188, v193
	ds_read_b128 v[188:191], v222
	ds_read_b128 v[204:207], v223
	s_waitcnt vmcnt(1) lgkmcnt(5)
	v_mfma_f32_32x32x16_bf16 v[0:15], v[172:175], v[164:167], v[0:15]
	s_waitcnt vmcnt(0) lgkmcnt(4)
	v_mfma_f32_32x32x16_bf16 v[0:15], v[176:179], v[168:171], v[0:15]
	v_add_u32_e32 v172, 0x1a000, v147
	v_add_u32_e32 v224, v172, v192
	v_add_u32_e32 v225, v172, v193
	ds_read_b128 v[172:175], v224
	ds_read_b128 v[176:179], v225
	s_waitcnt lgkmcnt(5)
	v_mfma_f32_32x32x16_bf16 v[16:31], v[180:183], v[164:167], v[16:31]
	s_waitcnt lgkmcnt(4)
	v_mfma_f32_32x32x16_bf16 v[16:31], v[184:187], v[168:171], v[16:31]
	v_add_u32_e32 v180, 0x1a800, v147
	v_add_u32_e32 v226, v180, v192
	v_add_u32_e32 v227, v180, v193
	ds_read_b128 v[180:183], v226
	ds_read_b128 v[184:187], v227
	s_waitcnt lgkmcnt(5)
	v_mfma_f32_32x32x16_bf16 v[34:49], v[188:191], v[164:167], v[34:49]
	s_waitcnt lgkmcnt(4)
	v_mfma_f32_32x32x16_bf16 v[34:49], v[204:207], v[168:171], v[34:49]
	v_add_u32_e32 v188, 0x1b000, v147
	v_add_u32_e32 v237, v188, v192
	v_add_u32_e32 v238, v188, v193
	ds_read_b128 v[188:191], v237
	ds_read_b128 v[204:207], v238
	s_waitcnt lgkmcnt(5)
	v_mfma_f32_32x32x16_bf16 v[66:81], v[172:175], v[164:167], v[66:81]
	s_waitcnt lgkmcnt(4)
	v_mfma_f32_32x32x16_bf16 v[66:81], v[176:179], v[168:171], v[66:81]
	v_add_u32_e32 v172, 0x1b800, v147
	v_add_u32_e32 v239, v172, v192
	v_add_u32_e32 v240, v172, v193
	ds_read_b128 v[172:175], v239
	ds_read_b128 v[176:179], v240
	s_waitcnt lgkmcnt(5)
	v_mfma_f32_32x32x16_bf16 v[98:113], v[180:183], v[164:167], v[98:113]
	s_waitcnt lgkmcnt(4)
	v_mfma_f32_32x32x16_bf16 v[98:113], v[184:187], v[168:171], v[98:113]
	v_add_u32_e32 v147, 0x1c000, v147
	v_add_u32_e32 v192, v147, v192
	v_add_u32_e32 v193, v147, v193
	ds_read_b128 v[180:183], v192
	ds_read_b128 v[184:187], v193
	s_waitcnt lgkmcnt(5)
	v_mfma_f32_32x32x16_bf16 v[114:129], v[188:191], v[164:167], v[114:129]
	s_waitcnt lgkmcnt(4)
	v_mfma_f32_32x32x16_bf16 v[114:129], v[204:207], v[168:171], v[114:129]
	s_waitcnt lgkmcnt(3)
	v_mfma_f32_32x32x16_bf16 v[82:97], v[172:175], v[164:167], v[82:97]
	s_waitcnt lgkmcnt(2)
	v_mfma_f32_32x32x16_bf16 v[82:97], v[176:179], v[168:171], v[82:97]
	s_waitcnt lgkmcnt(1)
	v_mfma_f32_32x32x16_bf16 v[50:65], v[180:183], v[164:167], v[50:65]
	s_waitcnt lgkmcnt(0)
	v_mfma_f32_32x32x16_bf16 v[50:65], v[184:187], v[168:171], v[50:65]
	ds_write_b128 v141, v[148:151]
	ds_write_b128 v141, v[152:155] offset:8192
	ds_write_b128 v141, v[156:159] offset:16384
	ds_write_b128 v141, v[160:163] offset:24576
	s_waitcnt lgkmcnt(0)
	s_barrier
	global_load_dwordx4 v[148:151], v[130:131], off offset:192
	global_load_dwordx4 v[152:155], v[132:133], off offset:192
	global_load_dwordx4 v[156:159], v[134:135], off offset:192
	global_load_dwordx4 v[160:163], v[136:137], off offset:192
	global_load_dwordx4 v[164:167], v[138:139], off offset:128
	global_load_dwordx4 v[168:171], v[138:139], off offset:160
	ds_read_b128 v[172:175], v142
	ds_read_b128 v[176:179], v143
	ds_read_b128 v[180:183], v144
	ds_read_b128 v[184:187], v145
	ds_read_b128 v[188:191], v146
	ds_read_b128 v[204:207], v195
	s_waitcnt vmcnt(1) lgkmcnt(5)
	v_mfma_f32_32x32x16_bf16 v[0:15], v[172:175], v[164:167], v[0:15]
	s_waitcnt vmcnt(0) lgkmcnt(4)
	v_mfma_f32_32x32x16_bf16 v[0:15], v[176:179], v[168:171], v[0:15]
	ds_read_b128 v[172:175], v208
	ds_read_b128 v[176:179], v209
	s_waitcnt lgkmcnt(5)
	v_mfma_f32_32x32x16_bf16 v[16:31], v[180:183], v[164:167], v[16:31]
	s_waitcnt lgkmcnt(4)
	v_mfma_f32_32x32x16_bf16 v[16:31], v[184:187], v[168:171], v[16:31]
	ds_read_b128 v[180:183], v210
	ds_read_b128 v[184:187], v211
	s_waitcnt lgkmcnt(5)
	v_mfma_f32_32x32x16_bf16 v[34:49], v[188:191], v[164:167], v[34:49]
	s_waitcnt lgkmcnt(4)
	v_mfma_f32_32x32x16_bf16 v[34:49], v[204:207], v[168:171], v[34:49]
	ds_read_b128 v[188:191], v212
	ds_read_b128 v[204:207], v213
	s_waitcnt lgkmcnt(5)
	v_mfma_f32_32x32x16_bf16 v[66:81], v[172:175], v[164:167], v[66:81]
	s_waitcnt lgkmcnt(4)
	v_mfma_f32_32x32x16_bf16 v[66:81], v[176:179], v[168:171], v[66:81]
	ds_read_b128 v[172:175], v214
	ds_read_b128 v[176:179], v215
	s_waitcnt lgkmcnt(5)
	v_mfma_f32_32x32x16_bf16 v[98:113], v[180:183], v[164:167], v[98:113]
	s_waitcnt lgkmcnt(4)
	v_mfma_f32_32x32x16_bf16 v[98:113], v[184:187], v[168:171], v[98:113]
	ds_read_b128 v[180:183], v216
	ds_read_b128 v[184:187], v217
	s_waitcnt lgkmcnt(5)
	v_mfma_f32_32x32x16_bf16 v[114:129], v[188:191], v[164:167], v[114:129]
	s_waitcnt lgkmcnt(4)
	v_mfma_f32_32x32x16_bf16 v[114:129], v[204:207], v[168:171], v[114:129]
	s_waitcnt lgkmcnt(3)
	v_mfma_f32_32x32x16_bf16 v[82:97], v[172:175], v[164:167], v[82:97]
	s_waitcnt lgkmcnt(2)
	v_mfma_f32_32x32x16_bf16 v[82:97], v[176:179], v[168:171], v[82:97]
	s_waitcnt lgkmcnt(1)
	v_mfma_f32_32x32x16_bf16 v[50:65], v[180:183], v[164:167], v[50:65]
	s_waitcnt lgkmcnt(0)
	v_mfma_f32_32x32x16_bf16 v[50:65], v[184:187], v[168:171], v[50:65]
	ds_write_b128 v141, v[148:151] offset:32768
	ds_write_b128 v141, v[152:155] offset:40960
	ds_write_b128 v141, v[156:159] offset:49152
	ds_write_b128 v141, v[160:163] offset:57344
	s_waitcnt lgkmcnt(0)
	s_barrier
; #define R2_LOADS(src, rstride, sl) do { _Pragma("unroll") for (int i = 0; i < 4; ++i) sr[i] = *(const v4u*)((src) + (size_t)(srow + 128 * i) * (rstride) + 32 * (sl) + 8 * sc4); } while (0)
; #define R2_STORES(bf) do { _Pragma("unroll") for (int i = 0; i < 4; ++i) *(LAS v4u*)(lds + (bf) * R2_SBUF + sso + 128 * i * 64) = sr[i]; } while (0)
;     ...
;           for (int sl = 0; sl < 8; ++sl) {
;               if (sl + 1 < 8) R2_LOADS(src, 256, sl + 1);
;               const bf16x8_t bq0 = *(const bf16x8_t*)(qg + 32 * sl), bq1 = *(const bf16x8_t*)(qg + 32 * sl + 16);
;               R2_SLICE(sl & 1, bq0, bq1);
;               if (sl + 1 < 8) R2_STORES((sl + 1) & 1);
;               __syncthreads();
;           } }
	global_load_dwordx4 v[148:151], v[130:131], off offset:256
	global_load_dwordx4 v[152:155], v[132:133], off offset:256
	global_load_dwordx4 v[156:159], v[134:135], off offset:256
	global_load_dwordx4 v[160:163], v[136:137], off offset:256
	global_load_dwordx4 v[164:167], v[138:139], off offset:192
	global_load_dwordx4 v[168:171], v[138:139], off offset:224
	ds_read_b128 v[172:175], v218
	ds_read_b128 v[176:179], v219
	ds_read_b128 v[180:183], v220
	ds_read_b128 v[184:187], v221
	ds_read_b128 v[188:191], v222
	ds_read_b128 v[204:207], v223
	s_waitcnt vmcnt(1) lgkmcnt(5)
	v_mfma_f32_32x32x16_bf16 v[0:15], v[172:175], v[164:167], v[0:15]
	s_waitcnt vmcnt(0) lgkmcnt(4)
	v_mfma_f32_32x32x16_bf16 v[0:15], v[176:179], v[168:171], v[0:15]
	ds_read_b128 v[172:175], v224
	ds_read_b128 v[176:179], v225
	s_waitcnt lgkmcnt(5)
	v_mfma_f32_32x32x16_bf16 v[16:31], v[180:183], v[164:167], v[16:31]
	s_waitcnt lgkmcnt(4)
	v_mfma_f32_32x32x16_bf16 v[16:31], v[184:187], v[168:171], v[16:31]
	ds_read_b128 v[180:183], v226
	ds_read_b128 v[184:187], v227
	s_waitcnt lgkmcnt(5)
	v_mfma_f32_32x32x16_bf16 v[34:49], v[188:191], v[164:167], v[34:49]
	s_waitcnt lgkmcnt(4)
	v_mfma_f32_32x32x16_bf16 v[34:49], v[204:207], v[168:171], v[34:49]
	ds_read_b128 v[188:191], v237
	ds_read_b128 v[204:207], v238
	s_waitcnt lgkmcnt(5)
	v_mfma_f32_32x32x16_bf16 v[66:81], v[172:175], v[164:167], v[66:81]
	s_waitcnt lgkmcnt(4)
	v_mfma_f32_32x32x16_bf16 v[66:81], v[176:179], v[168:171], v[66:81]
	ds_read_b128 v[172:175], v239
	ds_read_b128 v[176:179], v240
	s_waitcnt lgkmcnt(5)
	v_mfma_f32_32x32x16_bf16 v[98:113], v[180:183], v[164:167], v[98:113]
	s_waitcnt lgkmcnt(4)
	v_mfma_f32_32x32x16_bf16 v[98:113], v[184:187], v[168:171], v[98:113]
	ds_read_b128 v[180:183], v192
	ds_read_b128 v[184:187], v193
	s_waitcnt lgkmcnt(5)
	v_mfma_f32_32x32x16_bf16 v[114:129], v[188:191], v[164:167], v[114:129]
	s_waitcnt lgkmcnt(4)
	v_mfma_f32_32x32x16_bf16 v[114:129], v[204:207], v[168:171], v[114:129]
	s_waitcnt lgkmcnt(3)
	v_mfma_f32_32x32x16_bf16 v[82:97], v[172:175], v[164:167], v[82:97]
	s_waitcnt lgkmcnt(2)
	v_mfma_f32_32x32x16_bf16 v[82:97], v[176:179], v[168:171], v[82:97]
	s_waitcnt lgkmcnt(1)
	v_mfma_f32_32x32x16_bf16 v[50:65], v[180:183], v[164:167], v[50:65]
	s_waitcnt lgkmcnt(0)
	v_mfma_f32_32x32x16_bf16 v[50:65], v[184:187], v[168:171], v[50:65]
	ds_write_b128 v141, v[148:151]
	ds_write_b128 v141, v[152:155] offset:8192
	ds_write_b128 v141, v[156:159] offset:16384
	ds_write_b128 v141, v[160:163] offset:24576
	s_waitcnt lgkmcnt(0)
	s_barrier
	global_load_dwordx4 v[148:151], v[130:131], off offset:320
	global_load_dwordx4 v[152:155], v[132:133], off offset:320
	global_load_dwordx4 v[156:159], v[134:135], off offset:320
	global_load_dwordx4 v[160:163], v[136:137], off offset:320
	global_load_dwordx4 v[164:167], v[138:139], off offset:256
	global_load_dwordx4 v[168:171], v[138:139], off offset:288
	ds_read_b128 v[172:175], v142
	ds_read_b128 v[176:179], v143
	ds_read_b128 v[180:183], v144
	ds_read_b128 v[184:187], v145
	ds_read_b128 v[188:191], v146
	ds_read_b128 v[204:207], v195
	s_waitcnt vmcnt(1) lgkmcnt(5)
	v_mfma_f32_32x32x16_bf16 v[0:15], v[172:175], v[164:167], v[0:15]
	s_waitcnt vmcnt(0) lgkmcnt(4)
	v_mfma_f32_32x32x16_bf16 v[0:15], v[176:179], v[168:171], v[0:15]
	ds_read_b128 v[172:175], v208
	ds_read_b128 v[176:179], v209
	s_waitcnt lgkmcnt(5)
	v_mfma_f32_32x32x16_bf16 v[16:31], v[180:183], v[164:167], v[16:31]
	s_waitcnt lgkmcnt(4)
	v_mfma_f32_32x32x16_bf16 v[16:31], v[184:187], v[168:171], v[16:31]
	ds_read_b128 v[180:183], v210
	ds_read_b128 v[184:187], v211
	s_waitcnt lgkmcnt(5)
	v_mfma_f32_32x32x16_bf16 v[34:49], v[188:191], v[164:167], v[34:49]
	s_waitcnt lgkmcnt(4)
	v_mfma_f32_32x32x16_bf16 v[34:49], v[204:207], v[168:171], v[34:49]
	ds_read_b128 v[188:191], v212
	ds_read_b128 v[204:207], v213
	s_waitcnt lgkmcnt(5)
	v_mfma_f32_32x32x16_bf16 v[66:81], v[172:175], v[164:167], v[66:81]
	s_waitcnt lgkmcnt(4)
	v_mfma_f32_32x32x16_bf16 v[66:81], v[176:179], v[168:171], v[66:81]
	ds_read_b128 v[172:175], v214
	ds_read_b128 v[176:179], v215
	s_waitcnt lgkmcnt(5)
	v_mfma_f32_32x32x16_bf16 v[98:113], v[180:183], v[164:167], v[98:113]
	s_waitcnt lgkmcnt(4)
	v_mfma_f32_32x32x16_bf16 v[98:113], v[184:187], v[168:171], v[98:113]
	ds_read_b128 v[180:183], v216
	ds_read_b128 v[184:187], v217
	s_waitcnt lgkmcnt(5)
	v_mfma_f32_32x32x16_bf16 v[114:129], v[188:191], v[164:167], v[114:129]
	s_waitcnt lgkmcnt(4)
	v_mfma_f32_32x32x16_bf16 v[114:129], v[204:207], v[168:171], v[114:129]
	s_waitcnt lgkmcnt(3)
	v_mfma_f32_32x32x16_bf16 v[82:97], v[172:175], v[164:167], v[82:97]
	s_waitcnt lgkmcnt(2)
	v_mfma_f32_32x32x16_bf16 v[82:97], v[176:179], v[168:171], v[82:97]
	s_waitcnt lgkmcnt(1)
	v_mfma_f32_32x32x16_bf16 v[50:65], v[180:183], v[164:167], v[50:65]
	s_waitcnt lgkmcnt(0)
	v_mfma_f32_32x32x16_bf16 v[50:65], v[184:187], v[168:171], v[50:65]
	ds_write_b128 v141, v[148:151] offset:32768
	ds_write_b128 v141, v[152:155] offset:40960
	ds_write_b128 v141, v[156:159] offset:49152
	ds_write_b128 v141, v[160:163] offset:57344
	s_waitcnt lgkmcnt(0)
	s_barrier
; #define R2_LOADS(src, rstride, sl) do { _Pragma("unroll") for (int i = 0; i < 4; ++i) sr[i] = *(const v4u*)((src) + (size_t)(srow + 128 * i) * (rstride) + 32 * (sl) + 8 * sc4); } while (0)
; #define R2_STORES(bf) do { _Pragma("unroll") for (int i = 0; i < 4; ++i) *(LAS v4u*)(lds + (bf) * R2_SBUF + sso + 128 * i * 64) = sr[i]; } while (0)
;     ...
;           for (int sl = 0; sl < 8; ++sl) {
;               if (sl + 1 < 8) R2_LOADS(src, 256, sl + 1);
;               const bf16x8_t bq0 = *(const bf16x8_t*)(qg + 32 * sl), bq1 = *(const bf16x8_t*)(qg + 32 * sl + 16);
;               R2_SLICE(sl & 1, bq0, bq1);
;               if (sl + 1 < 8) R2_STORES((sl + 1) & 1);
;               __syncthreads();
;           } }
	global_load_dwordx4 v[148:151], v[130:131], off offset:384
	global_load_dwordx4 v[152:155], v[132:133], off offset:384
	global_load_dwordx4 v[156:159], v[134:135], off offset:384
	global_load_dwordx4 v[160:163], v[136:137], off offset:384
	global_load_dwordx4 v[164:167], v[138:139], off offset:320
	global_load_dwordx4 v[168:171], v[138:139], off offset:352
	ds_read_b128 v[172:175], v218
	ds_read_b128 v[176:179], v219
	ds_read_b128 v[180:183], v220
	ds_read_b128 v[184:187], v221
	ds_read_b128 v[188:191], v222
	ds_read_b128 v[204:207], v223
	s_waitcnt vmcnt(1) lgkmcnt(5)
	v_mfma_f32_32x32x16_bf16 v[0:15], v[172:175], v[164:167], v[0:15]
	s_waitcnt vmcnt(0) lgkmcnt(4)
	v_mfma_f32_32x32x16_bf16 v[0:15], v[176:179], v[168:171], v[0:15]
	ds_read_b128 v[172:175], v224
	ds_read_b128 v[176:179], v225
	s_waitcnt lgkmcnt(5)
	v_mfma_f32_32x32x16_bf16 v[16:31], v[180:183], v[164:167], v[16:31]
	s_waitcnt lgkmcnt(4)
	v_mfma_f32_32x32x16_bf16 v[16:31], v[184:187], v[168:171], v[16:31]
	ds_read_b128 v[180:183], v226
	ds_read_b128 v[184:187], v227
	s_waitcnt lgkmcnt(5)
	v_mfma_f32_32x32x16_bf16 v[34:49], v[188:191], v[164:167], v[34:49]
	s_waitcnt lgkmcnt(4)
	v_mfma_f32_32x32x16_bf16 v[34:49], v[204:207], v[168:171], v[34:49]
	ds_read_b128 v[188:191], v237
	ds_read_b128 v[204:207], v238
	s_waitcnt lgkmcnt(5)
	v_mfma_f32_32x32x16_bf16 v[66:81], v[172:175], v[164:167], v[66:81]
	s_waitcnt lgkmcnt(4)
	v_mfma_f32_32x32x16_bf16 v[66:81], v[176:179], v[168:171], v[66:81]
	ds_read_b128 v[172:175], v239
	ds_read_b128 v[176:179], v240
	s_waitcnt lgkmcnt(5)
	v_mfma_f32_32x32x16_bf16 v[98:113], v[180:183], v[164:167], v[98:113]
	s_waitcnt lgkmcnt(4)
	v_mfma_f32_32x32x16_bf16 v[98:113], v[184:187], v[168:171], v[98:113]
	ds_read_b128 v[180:183], v192
	ds_read_b128 v[184:187], v193
	s_waitcnt lgkmcnt(5)
	v_mfma_f32_32x32x16_bf16 v[114:129], v[188:191], v[164:167], v[114:129]
	s_waitcnt lgkmcnt(4)
	v_mfma_f32_32x32x16_bf16 v[114:129], v[204:207], v[168:171], v[114:129]
	s_waitcnt lgkmcnt(3)
	v_mfma_f32_32x32x16_bf16 v[82:97], v[172:175], v[164:167], v[82:97]
	s_waitcnt lgkmcnt(2)
	v_mfma_f32_32x32x16_bf16 v[82:97], v[176:179], v[168:171], v[82:97]
	s_waitcnt lgkmcnt(1)
	v_mfma_f32_32x32x16_bf16 v[50:65], v[180:183], v[164:167], v[50:65]
	s_waitcnt lgkmcnt(0)
	v_mfma_f32_32x32x16_bf16 v[50:65], v[184:187], v[168:171], v[50:65]
	ds_write_b128 v141, v[148:151]
	ds_write_b128 v141, v[152:155] offset:8192
	ds_write_b128 v141, v[156:159] offset:16384
	ds_write_b128 v141, v[160:163] offset:24576
	s_waitcnt lgkmcnt(0)
	s_barrier
	global_load_dwordx4 v[148:151], v[130:131], off offset:448
	s_nop 0
	global_load_dwordx4 v[130:133], v[132:133], off offset:448
	s_nop 0
	global_load_dwordx4 v[152:155], v[134:135], off offset:448
	s_nop 0
	global_load_dwordx4 v[134:137], v[136:137], off offset:448
	s_nop 0
	global_load_dwordx4 v[156:159], v[138:139], off offset:384
	global_load_dwordx4 v[160:163], v[138:139], off offset:416
	ds_read_b128 v[164:167], v142
	ds_read_b128 v[168:171], v143
	ds_read_b128 v[172:175], v144
	ds_read_b128 v[142:145], v145
	ds_read_b128 v[176:179], v146
	ds_read_b128 v[180:183], v195
	s_waitcnt vmcnt(1) lgkmcnt(5)
	v_mfma_f32_32x32x16_bf16 v[0:15], v[164:167], v[156:159], v[0:15]
	s_waitcnt vmcnt(0) lgkmcnt(4)
	v_mfma_f32_32x32x16_bf16 v[0:15], v[168:171], v[160:163], v[0:15]
	ds_read_b128 v[164:167], v208
	ds_read_b128 v[168:171], v209
	s_waitcnt lgkmcnt(5)
	v_mfma_f32_32x32x16_bf16 v[16:31], v[172:175], v[156:159], v[16:31]
	s_waitcnt lgkmcnt(4)
	v_mfma_f32_32x32x16_bf16 v[16:31], v[142:145], v[160:163], v[16:31]
	ds_read_b128 v[142:145], v210
	ds_read_b128 v[172:175], v211
	s_waitcnt lgkmcnt(5)
	v_mfma_f32_32x32x16_bf16 v[34:49], v[176:179], v[156:159], v[34:49]
	s_waitcnt lgkmcnt(4)
	v_mfma_f32_32x32x16_bf16 v[34:49], v[180:183], v[160:163], v[34:49]
	ds_read_b128 v[176:179], v212
	ds_read_b128 v[180:183], v213
	s_waitcnt lgkmcnt(5)
	v_mfma_f32_32x32x16_bf16 v[66:81], v[164:167], v[156:159], v[66:81]
	s_waitcnt lgkmcnt(4)
	v_mfma_f32_32x32x16_bf16 v[66:81], v[168:171], v[160:163], v[66:81]
	ds_read_b128 v[164:167], v214
	ds_read_b128 v[168:171], v215
	s_waitcnt lgkmcnt(5)
	v_mfma_f32_32x32x16_bf16 v[98:113], v[142:145], v[156:159], v[98:113]
	s_waitcnt lgkmcnt(4)
	v_mfma_f32_32x32x16_bf16 v[98:113], v[172:175], v[160:163], v[98:113]
	ds_read_b128 v[142:145], v216
	ds_read_b128 v[172:175], v217
	s_waitcnt lgkmcnt(5)
	v_mfma_f32_32x32x16_bf16 v[114:129], v[176:179], v[156:159], v[114:129]
	s_waitcnt lgkmcnt(4)
	v_mfma_f32_32x32x16_bf16 v[114:129], v[180:183], v[160:163], v[114:129]
	s_waitcnt lgkmcnt(3)
	v_mfma_f32_32x32x16_bf16 v[82:97], v[164:167], v[156:159], v[82:97]
	s_waitcnt lgkmcnt(2)
	v_mfma_f32_32x32x16_bf16 v[82:97], v[168:171], v[160:163], v[82:97]
	s_waitcnt lgkmcnt(1)
	v_mfma_f32_32x32x16_bf16 v[50:65], v[142:145], v[156:159], v[50:65]
	s_waitcnt lgkmcnt(0)
	v_mfma_f32_32x32x16_bf16 v[50:65], v[172:175], v[160:163], v[50:65]
	ds_write_b128 v141, v[148:151] offset:32768
	ds_write_b128 v141, v[130:133] offset:40960
	ds_write_b128 v141, v[152:155] offset:49152
	ds_write_b128 v141, v[134:137] offset:57344
	s_waitcnt lgkmcnt(0)
	s_barrier
; #define LAS __attribute__((address_space(3)))
; #define R2_LOADS(src, rstride, sl) do { _Pragma("unroll") for (int i = 0; i < 4; ++i) sr[i] = *(const v4u*)((src) + (size_t)(srow + 128 * i) * (rstride) + 32 * (sl) + 8 * sc4); } while (0)
; #define R2_STORES(bf) do { _Pragma("unroll") for (int i = 0; i < 4; ++i) *(LAS v4u*)(lds + (bf) * R2_SBUF + sso + 128 * i * 64) = sr[i]; } while (0)
;     ...
;           for (int sl = 0; sl < 8; ++sl) {
;               if (sl + 1 < 8) R2_LOADS(src, 256, sl + 1);
;               const bf16x8_t bq0 = *(const bf16x8_t*)(qg + 32 * sl), bq1 = *(const bf16x8_t*)(qg + 32 * sl + 16);
;               R2_SLICE(sl & 1, bq0, bq1);
;               if (sl + 1 < 8) R2_STORES((sl + 1) & 1);
;               __syncthreads();
;           } }
;         { R2_IDS const float qdec = __builtin_amdgcn_exp2f((float)(32 * nt + r + 1 + odd * 128) * lg2);
; #pragma unroll
;           for (int et = 0; et < 8; ++et)
; #pragma unroll
;               for (int i = 0; i < 16; ++i) acc[et][i] *= qdec; }
;         const int nmt = odd ? 4 + nt + 1 : nt + 1;
;         if (!(dry && (R2_SKIP & 2))) { R2_IDS
; #pragma unroll
;             for (int i = 0; i < 8; ++i) { const int ch = t_ + NTHR * i, n = ch >> 5, cc = ch & 31;
;                 *(LAS v4u*)(lds + R2_SOFF + n * 512 + ((cc ^ (n & 31)) * 16)) = *(const v4u*)(Q + ((size_t)(bh * SEQ + tq0 + n)) * 256 + cc * 8); }
;             __syncthreads();
	global_load_dwordx4 v[130:133], v[138:139], off offset:448
	global_load_dwordx4 v[134:137], v[138:139], off offset:480
	ds_read_b128 v[142:145], v218
	ds_read_b128 v[146:149], v219
	ds_read_b128 v[150:153], v220
	ds_read_b128 v[154:157], v221
	ds_read_b128 v[158:161], v222
	ds_read_b128 v[162:165], v223
	s_waitcnt vmcnt(1) lgkmcnt(5)
	v_mfma_f32_32x32x16_bf16 v[0:15], v[142:145], v[130:133], v[0:15]
	s_waitcnt vmcnt(0) lgkmcnt(4)
	v_mfma_f32_32x32x16_bf16 v[0:15], v[146:149], v[134:137], v[0:15]
	ds_read_b128 v[142:145], v224
	ds_read_b128 v[146:149], v225
	s_waitcnt lgkmcnt(5)
	v_mfma_f32_32x32x16_bf16 v[16:31], v[150:153], v[130:133], v[16:31]
	s_waitcnt lgkmcnt(4)
	v_mfma_f32_32x32x16_bf16 v[16:31], v[154:157], v[134:137], v[16:31]
	ds_read_b128 v[150:153], v226
	ds_read_b128 v[154:157], v227
	s_waitcnt lgkmcnt(5)
	v_mfma_f32_32x32x16_bf16 v[34:49], v[158:161], v[130:133], v[34:49]
	s_waitcnt lgkmcnt(4)
	v_mfma_f32_32x32x16_bf16 v[34:49], v[162:165], v[134:137], v[34:49]
	ds_read_b128 v[158:161], v237
	ds_read_b128 v[162:165], v238
	s_waitcnt lgkmcnt(5)
	v_mfma_f32_32x32x16_bf16 v[66:81], v[142:145], v[130:133], v[66:81]
	s_waitcnt lgkmcnt(4)
	v_mfma_f32_32x32x16_bf16 v[66:81], v[146:149], v[134:137], v[66:81]
	ds_read_b128 v[142:145], v239
	ds_read_b128 v[146:149], v240
	s_waitcnt lgkmcnt(5)
	v_mfma_f32_32x32x16_bf16 v[98:113], v[150:153], v[130:133], v[98:113]
	s_waitcnt lgkmcnt(4)
	v_mfma_f32_32x32x16_bf16 v[98:113], v[154:157], v[134:137], v[98:113]
	ds_read_b128 v[150:153], v192
	ds_read_b128 v[154:157], v193
	s_waitcnt lgkmcnt(5)
	v_mfma_f32_32x32x16_bf16 v[114:129], v[158:161], v[130:133], v[114:129]
	s_waitcnt lgkmcnt(4)
	v_mfma_f32_32x32x16_bf16 v[114:129], v[162:165], v[134:137], v[114:129]
	s_waitcnt lgkmcnt(3)
	v_mfma_f32_32x32x16_bf16 v[82:97], v[142:145], v[130:133], v[82:97]
	s_waitcnt lgkmcnt(2)
	v_mfma_f32_32x32x16_bf16 v[82:97], v[146:149], v[134:137], v[82:97]
	s_waitcnt lgkmcnt(1)
	v_mfma_f32_32x32x16_bf16 v[50:65], v[150:153], v[130:133], v[50:65]
	s_waitcnt lgkmcnt(0)
	v_mfma_f32_32x32x16_bf16 v[50:65], v[154:157], v[134:137], v[50:65]
	v_mov_b32_e32 v148, v33
	v_mov_b32_e32 v130, v33
	s_barrier
	v_mov_b32_e32 v133, v32
	v_lshlrev_b32_e32 v131, 4, v130
	v_add_u32_e32 v134, 0x200, v130
	v_and_b32_e32 v132, 0x1f0, v131
	v_ashrrev_i32_e32 v131, 5, v130
	v_ashrrev_i32_e32 v141, 5, v134
	v_lshl_add_u64 v[146:147], s[24:25], 0, v[132:133]
	v_add_u32_e32 v132, s19, v131
	v_add_u32_e32 v134, s19, v141
	v_ashrrev_i32_e32 v133, 31, v132
	v_ashrrev_i32_e32 v135, 31, v134
	v_lshlrev_b64 v[132:133], 9, v[132:133]
	v_lshlrev_b64 v[134:135], 9, v[134:135]
	v_lshl_add_u64 v[132:133], v[146:147], 0, v[132:133]
	v_lshl_add_u64 v[136:137], v[146:147], 0, v[134:135]
	v_add_u32_e32 v142, 0x400, v130
	global_load_dwordx4 v[132:135], v[132:133], off
	s_nop 0
	global_load_dwordx4 v[136:139], v[136:137], off
	v_ashrrev_i32_e32 v170, 5, v142
	v_add_u32_e32 v142, s19, v170
	v_ashrrev_i32_e32 v143, 31, v142
	v_add_u32_e32 v149, 0x600, v130
	v_lshlrev_b64 v[142:143], 9, v[142:143]
	v_ashrrev_i32_e32 v171, 5, v149
	v_lshl_add_u64 v[142:143], v[146:147], 0, v[142:143]
	v_add_u32_e32 v150, s19, v171
	global_load_dwordx4 v[142:145], v[142:143], off
	v_ashrrev_i32_e32 v151, 31, v150
	v_add_u32_e32 v149, 0x800, v130
	v_lshlrev_b64 v[150:151], 9, v[150:151]
	v_ashrrev_i32_e32 v172, 5, v149
	v_lshl_add_u64 v[150:151], v[146:147], 0, v[150:151]
	v_add_u32_e32 v154, s19, v172
	global_load_dwordx4 v[150:153], v[150:151], off
	v_ashrrev_i32_e32 v155, 31, v154
	v_add_u32_e32 v149, 0xa00, v130
	v_lshlrev_b64 v[154:155], 9, v[154:155]
	v_ashrrev_i32_e32 v173, 5, v149
	v_lshl_add_u64 v[154:155], v[146:147], 0, v[154:155]
	v_add_u32_e32 v158, s19, v173
	global_load_dwordx4 v[154:157], v[154:155], off
	v_ashrrev_i32_e32 v159, 31, v158
	v_add_u32_e32 v149, 0xc00, v130
	v_lshlrev_b64 v[158:159], 9, v[158:159]
	v_ashrrev_i32_e32 v174, 5, v149
	v_lshl_add_u64 v[158:159], v[146:147], 0, v[158:159]
	v_add_u32_e32 v162, s19, v174
	v_add_u32_e32 v149, 0xe00, v130
	global_load_dwordx4 v[158:161], v[158:159], off
	v_ashrrev_i32_e32 v163, 31, v162
	v_ashrrev_i32_e32 v175, 5, v149
	v_lshlrev_b64 v[162:163], 9, v[162:163]
	v_add_u32_e32 v166, s19, v175
	v_lshl_add_u64 v[162:163], v[146:147], 0, v[162:163]
	v_ashrrev_i32_e32 v167, 31, v166
	global_load_dwordx4 v[162:165], v[162:163], off
	v_lshlrev_b64 v[166:167], 9, v[166:167]
	v_lshl_add_u64 v[146:147], v[146:147], 0, v[166:167]
	global_load_dwordx4 v[166:169], v[146:147], off
	v_lshlrev_b32_e32 v147, 9, v131
	v_xor_b32_e32 v131, v131, v130
	v_lshlrev_b32_e32 v131, 4, v131
	v_lshlrev_b32_e32 v149, 9, v141
	v_xor_b32_e32 v141, v141, v130
	v_and_b32_e32 v131, 0x1f0, v131
	v_lshlrev_b32_e32 v141, 4, v141
	v_add3_u32 v131, s93, v147, v131
	v_and_b32_e32 v141, 0x1f0, v141
	v_add3_u32 v141, s93, v149, v141
	s_mov_b32 s19, 0x800000
	v_cmp_gt_f32_e32 vcc, s19, v140
	s_and_b64 s[34:35], vcc, exec
	s_cselect_b32 s19, 32, 0
	s_cmp_eq_u32 s40, 0
	v_ldexp_f32 v140, v140, s19
	s_cselect_b64 s[34:35], -1, 0
	v_log_f32_e32 v140, v140
	s_and_b64 s[52:53], s[34:35], exec
	s_cselect_b32 s19, 1, 5
	v_cndmask_b32_e32 v146, 0, v236, vcc
	s_add_i32 s19, s19, s45
	s_waitcnt vmcnt(7)
	ds_write_b128 v131, v[132:135]
	s_waitcnt vmcnt(6)
	ds_write_b128 v141, v[136:139]
	v_xor_b32_e32 v132, v170, v130
	v_lshlrev_b32_e32 v132, 4, v132
	v_lshlrev_b32_e32 v131, 9, v170
	v_and_b32_e32 v132, 0x1f0, v132
	v_add3_u32 v131, s93, v131, v132
	v_xor_b32_e32 v132, v171, v130
	v_lshlrev_b32_e32 v132, 4, v132
	v_and_b32_e32 v132, 0x1f0, v132
	s_waitcnt vmcnt(5)
	ds_write_b128 v131, v[142:145]
	v_lshlrev_b32_e32 v131, 9, v171
	v_add3_u32 v131, s93, v131, v132
	v_xor_b32_e32 v132, v172, v130
	v_lshlrev_b32_e32 v132, 4, v132
	v_and_b32_e32 v132, 0x1f0, v132
	v_sub_f32_e32 v149, v140, v146
	s_waitcnt vmcnt(4)
	ds_write_b128 v131, v[150:153]
	v_lshlrev_b32_e32 v131, 9, v172
	v_add3_u32 v131, s93, v131, v132
	v_xor_b32_e32 v132, v173, v130
	v_lshlrev_b32_e32 v132, 4, v132
	v_and_b32_e32 v132, 0x1f0, v132
	s_cmp_ge_i32 s46, s19
	s_waitcnt vmcnt(3)
	ds_write_b128 v131, v[154:157]
	v_lshlrev_b32_e32 v131, 9, v173
	v_add3_u32 v131, s93, v131, v132
	v_xor_b32_e32 v132, v174, v130
	v_lshlrev_b32_e32 v132, 4, v132
	v_and_b32_e32 v132, 0x1f0, v132
	s_waitcnt vmcnt(2)
	ds_write_b128 v131, v[158:161]
	v_lshlrev_b32_e32 v131, 9, v174
	v_add3_u32 v131, s93, v131, v132
	v_xor_b32_e32 v132, v175, v130
	v_lshlrev_b32_e32 v132, 4, v132
	v_and_b32_e32 v132, 0x1f0, v132
	s_waitcnt vmcnt(1)
	ds_write_b128 v131, v[162:165]
	v_lshlrev_b32_e32 v131, 9, v175
	v_add3_u32 v131, s93, v131, v132
	s_waitcnt vmcnt(0)
	ds_write_b128 v131, v[166:169]
	s_waitcnt lgkmcnt(0)
	s_barrier
; #define LAS __attribute__((address_space(3)))
; #define MFMA32(a, b, c) __builtin_amdgcn_mfma_f32_32x32x16_bf16((a), (b), (c), 0, 0, 0)
;     ...
;             const LAS unsigned char* qrow = lds + R2_SOFF + (32 * nt + r) * 512;
;             for (int mt = eh; mt < nmt; mt += 2) {
;                 f32x16 p;
; #pragma unroll
;                 for (int i = 0; i < 16; ++i) p[i] = 0.f;
;                 const bf16* kb = K + ((size_t)(bh * SEQ + tk0 + 32 * mt + r)) * 256 + 8 * hh;
; #pragma unroll
;                 for (int kh = 0; kh < 2; ++kh) { bf16x8_t kf[8];
; #pragma unroll
;                     for (int jj = 0; jj < 8; ++jj) kf[jj] = *(const bf16x8_t*)(kb + (8 * kh + jj) * 16);
; #pragma unroll
;                     for (int jj = 0; jj < 8; ++jj) p = MFMA32(kf[jj], *(const LAS bf16x8_t*)(qrow + (((2 * (8 * kh + jj) + hh) ^ r) * 16)), p); }
;                 const int nq = tq0 + 32 * nt + r, mk = tk0 + 32 * mt + 4 * hh;
	s_cbranch_scc1 .LBB0_721
	v_and_b32_e32 v150, 31, v130
	v_bfe_u32 v135, v130, 5, 1
	v_or_b32_e32 v132, s47, v150
	v_lshrrev_b32_e32 v134, 5, v130
	v_lshlrev_b32_e32 v130, 4, v135
	v_mov_b32_e32 v131, v32
	v_bitop3_b32 v151, v135, v150, 24 bitop3:0x36
	v_lshl_add_u64 v[146:147], s[26:27], 0, v[130:131]
	v_lshlrev_b32_e32 v130, 2, v135
	v_mul_u32_u24_e32 v131, 0x108, v132
	v_lshlrev_b32_e32 v166, 4, v151
	v_bitop3_b32 v151, v135, v150, 26 bitop3:0x36
	v_lshl_add_u32 v133, v132, 9, s93
	v_bitop3_b32 v132, v134, v150, 1 bitop3:0x6c
	v_bitop3_b32 v134, v135, v150, 2 bitop3:0x36
	v_bitop3_b32 v136, v135, v150, 4 bitop3:0x36
	v_bitop3_b32 v137, v135, v150, 6 bitop3:0x36
	v_bitop3_b32 v138, v135, v150, 8 bitop3:0x36
	v_bitop3_b32 v139, v135, v150, 10 bitop3:0x36
	v_bitop3_b32 v140, v135, v150, 12 bitop3:0x36
	v_bitop3_b32 v141, v135, v150, 14 bitop3:0x36
	v_bitop3_b32 v142, v135, v150, 16 bitop3:0x36
	v_bitop3_b32 v143, v135, v150, 18 bitop3:0x36
	v_bitop3_b32 v144, v135, v150, 20 bitop3:0x36
	v_bitop3_b32 v145, v135, v150, 22 bitop3:0x36
	v_lshlrev_b32_e32 v167, 4, v151
	v_bitop3_b32 v151, v135, v150, 28 bitop3:0x36
	v_bitop3_b32 v135, v135, v150, 30 bitop3:0x36
	v_add3_u32 v131, s91, v131, v130
	s_add_i32 s49, s18, s5
	s_add_i32 s52, s91, s6
	v_lshlrev_b32_e32 v132, 4, v132
	v_lshlrev_b32_e32 v134, 4, v134
	v_lshlrev_b32_e32 v136, 4, v136
	v_lshlrev_b32_e32 v137, 4, v137
	v_lshlrev_b32_e32 v138, 4, v138
	v_lshlrev_b32_e32 v139, 4, v139
	v_lshlrev_b32_e32 v140, 4, v140
	v_lshlrev_b32_e32 v141, 4, v141
	v_lshlrev_b32_e32 v142, 4, v142
	v_lshlrev_b32_e32 v143, 4, v143
	v_lshlrev_b32_e32 v144, 4, v144
	v_lshlrev_b32_e32 v145, 4, v145
	v_lshlrev_b32_e32 v168, 4, v151
	v_lshlrev_b32_e32 v135, 4, v135
	v_lshl_add_u32 v151, v131, 1, 0
	v_sub_u32_e32 v131, s49, v130
	s_add_i32 s49, s47, s5
	v_add_u32_e32 v130, s52, v130
	v_subrev_u32_e32 v152, s6, v131
	v_sub_u32_e32 v153, s49, v130
	s_add_i32 s41, s52, s41
	v_add_u32_e32 v154, v133, v132
	v_add_u32_e32 v155, v133, v134
	v_add_u32_e32 v156, v133, v136
	v_add_u32_e32 v157, v133, v137
	v_add_u32_e32 v158, v133, v138
	v_add_u32_e32 v159, v133, v139
	v_add_u32_e32 v160, v133, v140
	v_add_u32_e32 v161, v133, v141
	v_add_u32_e32 v162, v133, v142
	v_add_u32_e32 v163, v133, v143
	v_add_u32_e32 v164, v133, v144
	v_add_u32_e32 v165, v133, v145
	v_add_u32_e32 v166, v133, v166
	v_add_u32_e32 v167, v133, v167
	v_add_u32_e32 v168, v133, v168
	v_add_u32_e32 v169, v133, v135
	s_mov_b32 s49, s46
	s_nop 0

; #define PG8_WAIT_V(n) asm volatile("s_waitcnt vmcnt(" #n ")" ::: "memory")
; #define PG8_BAR __builtin_amdgcn_s_barrier()
; template <class Epi, class Sched, bool ALIGN_EPI = false, bool SP2 = false>
; __device__ __forceinline__ void gemm_phase(PG8_LAS unsigned char* lds, const Gemm g, const Sched& S, const Epi& E) {
;     ...
;     PG8_WAIT_V(0);
;     if constexpr (!ALIGN_EPI) { if (wr == 0) PG8_BAR; }
;     PG8_BAR;
.LBB0_829:
	s_nop 0
	s_waitcnt vmcnt(0)
	s_cmpk_gt_u32 s94, 0xff
	s_cbranch_scc1 .LBB0_831
	s_barrier

; #define PG8_WAIT_V(n) asm volatile("s_waitcnt vmcnt(" #n ")" ::: "memory")
; #define PG8_BAR __builtin_amdgcn_s_barrier()
; #define LAS __attribute__((address_space(3)))
; __device__ __forceinline__ unsigned pk2(float lo, float hi) { return (unsigned)f2bf1(lo) | ((unsigned)f2bf1(hi) << 16); }
; #define ITEM_(i) item_plain(W, K, N, (i))
; #define ITEM_(i) item_gu(Wg, Wu, (i))
; template <class Epi, class Sched, bool ALIGN_EPI = false, bool SP2 = false>
; __device__ __forceinline__ void gemm_phase(PG8_LAS unsigned char* lds, const Gemm g, const Sched& S, const Epi& E) {
;     ...
;     PG8_WAIT_V(0);
;     if constexpr (!ALIGN_EPI) { if (wr == 0) PG8_BAR; }
;     PG8_BAR;
; __device__ __forceinline__ void tr_load(float (&v)[32], const TrItem& t, int lane) {
; #pragma unroll
;     for (int i = 0; i < 32; ++i) { const int kk = 2 * i + (lane >> 5); v[i] = t.W[(size_t)(t.k0 + kk) * t.Nsrc + t.c0 + (lane & 31)]; }
; }
; __device__ __forceinline__ void tr_finish(const float (&v)[32], const TrItem& t, bf16* WT, LAS float* scr, int lane) {
; #pragma unroll
;     for (int i = 0; i < 32; ++i) { const int kk = 2 * i + (lane >> 5); scr[kk * 33 + (lane & 31)] = v[i]; }
;     asm volatile("s_waitcnt lgkmcnt(0)" ::: "memory");
;     const int c = lane & 7;
; #pragma unroll
;     for (int j = 0; j < 4; ++j) { const int n = (lane >> 3) + 8 * j; const LAS float* s = scr + (8 * c) * 33 + n;
;         v4u o; o.x = pk2(s[0 * 33], s[1 * 33]); o.y = pk2(s[2 * 33], s[3 * 33]); o.z = pk2(s[4 * 33], s[5 * 33]); o.w = pk2(s[6 * 33], s[7 * 33]);
;         *(v4u*)(WT + (size_t)(t.r0 + n) * t.K + t.k0 + 8 * c) = o; }
;     asm volatile("s_waitcnt lgkmcnt(0)" ::: "memory");
; }
; __device__ __forceinline__ void conv_plain(const float* W, int K, int N, bf16* WT, LAS float* scr, int gw, int ngw, int lane) {
;     ...
;     for (int rep_ = 0; rep_ < ((PROBE_DUP & 256) ? 2 : 1); ++rep_) CONV_LOOP((K / 64) * (N / 32), ITEM_, WT);
.LBB0_942:
	s_nop 0
	s_waitcnt vmcnt(0)
	v_readlane_b32 s56, v255, 4
	v_readlane_b32 s58, v255, 6
	v_readlane_b32 s52, v255, 8
	v_readlane_b32 s57, v255, 5
	v_readlane_b32 s59, v255, 7
	v_readlane_b32 s53, v255, 9
	v_readlane_b32 s55, v255, 10
	s_barrier
	v_readlane_b32 s5, v254, 0
	s_nop 3
	s_cmp_lt_u32 s5, 0x80
	s_cbranch_scc1 .Lcv_skip
	s_mov_b64 s[44:45], s[6:7]
	s_cmp_lt_i32 s16, 3
	s_cbranch_scc0 .Lcv_done
	s_add_i32 s18, s16, 1
	s_waitcnt lgkmcnt(0)
	s_mov_b64 s[26:27], s[56:57]
	s_waitcnt vmcnt(0)
	v_mov_b32_e32 v0, v228
	v_readlane_b32 s5, v254, 0
	s_load_dwordx2 s[24:25], s[26:27], 0x68
	s_lshl_b32 s5, s5, 3
	v_readfirstlane_b32 s4, v0
	s_ashr_i32 s4, s4, 6
	s_add_i32 s17, s5, s4
	s_addk_i32 s17, 0xfc00
	s_lshl_b32 s4, s4, 14
	v_bfe_u32 v33, v0, 5, 1
	v_and_b32_e32 v1, 31, v0
	v_bfe_u32 v45, v0, 3, 3
	v_lshlrev_b32_e32 v0, 3, v0
	s_add_i32 s4, s4, 0
	v_lshlrev_b32_e32 v34, 2, v1
	v_mul_u32_u24_e32 v1, 0x84, v33
	v_and_b32_e32 v50, 56, v0
	s_ashr_i32 s28, s18, 1
	v_add3_u32 v44, s4, v34, v1
	v_mul_u32_u24_e32 v0, 0x84, v50
	v_lshlrev_b32_e32 v1, 2, v45
	s_ashr_i32 s29, s28, 31
	v_add3_u32 v46, s4, v0, v1
	v_readlane_b32 s4, v255, 11
	s_waitcnt lgkmcnt(0)
	s_add_u32 s30, s24, 0x200000
	v_readlane_b32 s5, v255, 12
	s_addc_u32 s31, s25, 0
	v_or_b32_e32 v47, 8, v45
	v_or_b32_e32 v48, 16, v45
	v_or_b32_e32 v49, 24, v45
	s_mov_b64 s[6:7], -1
	s_and_b64 vcc, exec, s[4:5]
	s_cbranch_vccz .LcvA_b1032
	s_cmpk_gt_i32 s17, 0xbff
	s_cbranch_scc1 .LcvA_b1022
	s_load_dwordx2 s[4:5], s[26:27], 0x10
	s_mul_i32 s7, s28, 0x1800000
	s_mul_hi_i32 s6, s28, 0x1800000
	v_mov_b32_e32 v35, v32
	s_waitcnt lgkmcnt(0)
	s_add_u32 s4, s4, s7
	s_addc_u32 s5, s5, s6
	v_lshl_add_u64 v[36:37], s[4:5], 0, v[34:35]
	s_mul_hi_i32 s4, s17, 0x2aaaaaab
	s_lshr_b32 s5, s4, 31
	s_ashr_i32 s4, s4, 5
	s_add_i32 s5, s4, s5
	s_mul_i32 s4, s5, 0xc0
	s_sub_i32 s4, s17, s4
	s_lshl_b32 s4, s4, 5
	v_lshl_or_b32 v35, s5, 6, v33
	s_ashr_i32 s5, s4, 31
	v_lshl_add_u64 v[38:39], s[4:5], 2, v[36:37]
	v_mad_i64_i32 v[0:1], s[4:5], v35, s54, v[38:39]
	global_load_dword v0, v[0:1], off
	v_or_b32_e32 v1, 2, v35
	v_mad_i64_i32 v[2:3], s[4:5], v1, s54, v[38:39]
	global_load_dword v1, v[2:3], off
	v_or_b32_e32 v2, 4, v35
	v_mad_i64_i32 v[2:3], s[4:5], v2, s54, v[38:39]
	global_load_dword v2, v[2:3], off
	v_or_b32_e32 v3, 6, v35
	v_mad_i64_i32 v[4:5], s[4:5], v3, s54, v[38:39]
	global_load_dword v3, v[4:5], off
	v_or_b32_e32 v4, 8, v35
	v_mad_i64_i32 v[4:5], s[4:5], v4, s54, v[38:39]
	global_load_dword v4, v[4:5], off
	v_or_b32_e32 v5, 10, v35
	v_mad_i64_i32 v[6:7], s[4:5], v5, s54, v[38:39]
	global_load_dword v5, v[6:7], off
	v_or_b32_e32 v6, 12, v35
	v_mad_i64_i32 v[6:7], s[4:5], v6, s54, v[38:39]
	global_load_dword v6, v[6:7], off
	v_or_b32_e32 v7, 14, v35
	v_mad_i64_i32 v[8:9], s[4:5], v7, s54, v[38:39]
	global_load_dword v7, v[8:9], off
	v_or_b32_e32 v8, 16, v35
	v_mad_i64_i32 v[8:9], s[4:5], v8, s54, v[38:39]
	global_load_dword v8, v[8:9], off
	v_or_b32_e32 v9, 18, v35
	v_mad_i64_i32 v[10:11], s[4:5], v9, s54, v[38:39]
	global_load_dword v9, v[10:11], off
	v_or_b32_e32 v10, 20, v35
	v_mad_i64_i32 v[10:11], s[4:5], v10, s54, v[38:39]
	global_load_dword v10, v[10:11], off
	v_or_b32_e32 v11, 22, v35
	v_mad_i64_i32 v[12:13], s[4:5], v11, s54, v[38:39]
	global_load_dword v11, v[12:13], off
	v_or_b32_e32 v12, 24, v35
	v_mad_i64_i32 v[12:13], s[4:5], v12, s54, v[38:39]
	global_load_dword v12, v[12:13], off
	v_or_b32_e32 v13, 26, v35
	v_mad_i64_i32 v[14:15], s[4:5], v13, s54, v[38:39]
	global_load_dword v13, v[14:15], off
	v_or_b32_e32 v14, 28, v35
	v_mad_i64_i32 v[14:15], s[4:5], v14, s54, v[38:39]
	global_load_dword v14, v[14:15], off
	v_or_b32_e32 v15, 30, v35
	v_mad_i64_i32 v[16:17], s[4:5], v15, s54, v[38:39]
	global_load_dword v15, v[16:17], off
	v_or_b32_e32 v16, 32, v35
	v_mad_i64_i32 v[16:17], s[4:5], v16, s54, v[38:39]
	global_load_dword v16, v[16:17], off
	v_or_b32_e32 v17, 34, v35
	v_mad_i64_i32 v[18:19], s[4:5], v17, s54, v[38:39]
	global_load_dword v17, v[18:19], off
	v_or_b32_e32 v18, 36, v35
	v_mad_i64_i32 v[18:19], s[4:5], v18, s54, v[38:39]
	global_load_dword v18, v[18:19], off
	v_or_b32_e32 v19, 38, v35
	v_mad_i64_i32 v[20:21], s[4:5], v19, s54, v[38:39]
	global_load_dword v19, v[20:21], off
	v_or_b32_e32 v20, 40, v35
	v_mad_i64_i32 v[20:21], s[4:5], v20, s54, v[38:39]
	global_load_dword v20, v[20:21], off
	v_or_b32_e32 v21, 42, v35
	v_mad_i64_i32 v[22:23], s[4:5], v21, s54, v[38:39]
	global_load_dword v21, v[22:23], off
	v_or_b32_e32 v22, 44, v35
	v_mad_i64_i32 v[22:23], s[4:5], v22, s54, v[38:39]
	global_load_dword v22, v[22:23], off
	v_or_b32_e32 v23, 46, v35
	v_mad_i64_i32 v[24:25], s[4:5], v23, s54, v[38:39]
	global_load_dword v23, v[24:25], off
	v_or_b32_e32 v24, 48, v35
	v_mad_i64_i32 v[24:25], s[4:5], v24, s54, v[38:39]
	global_load_dword v24, v[24:25], off
	v_or_b32_e32 v25, 50, v35
	v_mad_i64_i32 v[26:27], s[4:5], v25, s54, v[38:39]
	global_load_dword v25, v[26:27], off
	v_or_b32_e32 v26, 52, v35
	v_mad_i64_i32 v[26:27], s[4:5], v26, s54, v[38:39]
	global_load_dword v26, v[26:27], off
	v_or_b32_e32 v27, 54, v35
	v_mad_i64_i32 v[28:29], s[4:5], v27, s54, v[38:39]
	global_load_dword v27, v[28:29], off
	v_or_b32_e32 v28, 56, v35
	v_mad_i64_i32 v[28:29], s[4:5], v28, s54, v[38:39]
	global_load_dword v28, v[28:29], off
	v_or_b32_e32 v29, 58, v35
	v_mad_i64_i32 v[30:31], s[4:5], v29, s54, v[38:39]
	global_load_dword v29, v[30:31], off
	v_or_b32_e32 v30, 60, v35
	v_mad_i64_i32 v[30:31], s[4:5], v30, s54, v[38:39]
	global_load_dword v30, v[30:31], off
	v_or_b32_e32 v31, 62, v35
	v_mad_i64_i32 v[38:39], s[4:5], v31, s54, v[38:39]
	global_load_dword v31, v[38:39], off
	v_lshlrev_b32_e32 v38, 1, v50
	s_mov_b32 s4, s17
	s_branch .LcvA_b1017
